# GEMM prologues: second K-tile's LDS-DMA stages issued before the first wait (vmcnt(2) -> vmcnt(8)), one cold round trip instead of two
# baseline (speedup 1.0000x reference)
; #define PG8_STAGE(bufoff, gbase, voff) do { _Pragma("unroll") for (int _i = 0; _i < 2; ++_i) \
;         __builtin_amdgcn_global_load_lds((const unsigned*)((const char*)(gbase) + (voff)[_i]), (LAS unsigned*)(lds + (bufoff) + ldsw + _i * 8192), 16, 0, 0); } while (0)
; #define PG8_WAIT_V(n) asm volatile("s_waitcnt vmcnt(" #n ")" ::: "memory")
; #define PG8_BAR __builtin_amdgcn_s_barrier()
; template <class Epi>
; __device__ __forceinline__ void gemm_phase(LAS unsigned char* lds, const Gemm g, const Sched& S, const Epi& E) {
;     ...
;     PG8_STAGE(PG8_SB(0, 0), cB, voffB); PG8_STAGE(PG8_SB(0, 1), cB + hstepB, voffB); PG8_STAGE(PG8_SA(0, 0), cA, voffA); PG8_STAGE(PG8_SA(0, 1), cA + hstepA, voffA);
;     if (wr == 1) PG8_BAR;
;     PG8_WAIT_V(2); PG8_BAR;
;     PG8_STAGE(PG8_SB(1, 0), cB + kstep, voffB); PG8_STAGE(PG8_SA(1, 0), cA + kstep, voffA); PG8_STAGE(PG8_SB(1, 1), cB + hstepB + kstep, voffB);
;     PG8_WAIT_V(6); PG8_BAR;
.LBB0_153:
	s_add_u32 s2, s34, 0x9e00000
	s_addc_u32 s3, s35, 0
	s_lshl_b32 s4, s4, 5
	s_and_b32 s15, s4, 0x60
	s_mov_b64 s[4:5], 0x80
	s_add_i32 m0, s29, 0x18000
	v_lshl_add_u64 v[6:7], v[6:7], 0, s[4:5]
	s_lshl_b32 s14, s7, 13
	s_lshl_b32 s20, s15, 7
	global_load_lds_dwordx4 v[6:7], off
	v_lshl_add_u64 v[4:5], v[4:5], 0, s[4:5]
	s_add_i32 m0, s29, 0x1a000
	s_add_i32 s58, s29, 0x8000
	s_add_i32 s59, s29, 0xa000
	global_load_lds_dwordx4 v[4:5], off
	v_lshl_add_u64 v[0:1], v[0:1], 0, s[4:5]
	s_mov_b32 m0, s58
	s_add_u32 s8, s44, 0x40080
	global_load_lds_dwordx4 v[0:1], off
	v_lshl_add_u64 v[0:1], v[2:3], 0, s[4:5]
	s_mov_b32 m0, s59
	s_addc_u32 s9, s45, 0
	global_load_lds_dwordx4 v[0:1], off
	s_add_i32 m0, s29, 0x1c000
	v_lshl_add_u64 v[0:1], s[8:9], 0, v[130:131]
	global_load_lds_dwordx4 v[0:1], off
	v_lshl_add_u64 v[0:1], s[8:9], 0, v[134:135]
	s_add_i32 m0, s29, 0x1e000
	s_cmpk_lt_u32 s6, 0x100
	global_load_lds_dwordx4 v[0:1], off
	s_waitcnt vmcnt(8)
	s_barrier
	v_lshrrev_b32_e32 v1, 1, v8
	v_and_b32_e32 v1, 24, v1
	v_and_b32_e32 v0, 15, v8
	v_lshlrev_b32_e32 v2, 1, v1
	v_lshl_or_b32 v142, s7, 6, v0
	v_lshl_or_b32 v0, v0, 6, v2
	v_lshlrev_b32_e32 v2, 2, v8
	v_and_b32_e32 v2, 32, v2
	v_bitop3_b32 v3, v0, s14, v2 bitop3:0xde
	v_bitop3_b32 v143, v0, s20, v2 bitop3:0xde
	v_lshlrev_b32_e32 v0, 14, v9
	v_and_b32_e32 v0, 0xffff8000, v0
	v_or_b32_e32 v144, s15, v1
	v_lshl_add_u32 v0, v10, 11, v0
	v_and_b32_e32 v1, 1, v9
	v_lshl_or_b32 v0, v1, 6, v0
	v_lshl_add_u32 v136, v11, 1, v0
	v_lshlrev_b32_e32 v0, 14, v12
	v_and_b32_e32 v0, 0xffff8000, v0
	s_waitcnt vmcnt(6)
	v_lshl_add_u32 v0, v13, 11, v0
	v_and_b32_e32 v1, 1, v12
	s_cselect_b64 s[6:7], -1, 0
	v_lshl_or_b32 v0, v1, 6, v0
	s_add_i32 s60, 0, 0x10000
	s_add_i32 s61, 0, 0x14000
	v_mov_b32_e32 v137, v131
	v_lshl_add_u32 v138, v14, 1, v0
	v_mov_b32_e32 v139, v131
	v_add_u32_e32 v145, s60, v143
	v_add_u32_e32 v146, s61, v143
	v_add_u32_e32 v147, 0, v3
	s_movk_i32 s62, 0x4080
	s_movk_i32 s63, 0x1600
	s_barrier
	s_branch .LBB0_156

; #define PG8_STAGE(bufoff, gbase, voff) do { _Pragma("unroll") for (int _i = 0; _i < 2; ++_i) \
;         __builtin_amdgcn_global_load_lds((const unsigned*)((const char*)(gbase) + (voff)[_i]), (LAS unsigned*)(lds + (bufoff) + ldsw + _i * 8192), 16, 0, 0); } while (0)
; #define PG8_WAIT_V(n) asm volatile("s_waitcnt vmcnt(" #n ")" ::: "memory")
; #define PG8_BAR __builtin_amdgcn_s_barrier()
; template <class Epi>
; __device__ __forceinline__ void gemm_phase(LAS unsigned char* lds, const Gemm g, const Sched& S, const Epi& E) {
;     ...
;     PG8_STAGE(PG8_SB(0, 0), cB, voffB); PG8_STAGE(PG8_SB(0, 1), cB + hstepB, voffB); PG8_STAGE(PG8_SA(0, 0), cA, voffA); PG8_STAGE(PG8_SA(0, 1), cA + hstepA, voffA);
;     if (wr == 1) PG8_BAR;
;     PG8_WAIT_V(2); PG8_BAR;
;     PG8_STAGE(PG8_SB(1, 0), cB + kstep, voffB); PG8_STAGE(PG8_SA(1, 0), cA + kstep, voffA); PG8_STAGE(PG8_SB(1, 1), cB + hstepB + kstep, voffB);
;     PG8_WAIT_V(6); PG8_BAR;
.LBB0_195:
	s_lshl_b32 s2, s2, 5
	s_and_b32 s15, s2, 0x60
	s_lshl_b32 s14, s7, 13
	s_lshl_b32 s20, s15, 7
	s_add_u32 s2, s34, 0x3300000
	s_mov_b64 s[4:5], 0x80
	s_addc_u32 s3, s35, 0
	s_add_i32 m0, s29, 0x18000
	v_lshl_add_u64 v[6:7], v[6:7], 0, s[4:5]
	global_load_lds_dwordx4 v[6:7], off
	v_lshl_add_u64 v[4:5], v[4:5], 0, s[4:5]
	s_add_i32 m0, s29, 0x1a000
	s_add_i32 s59, s29, 0x8000
	s_add_i32 s60, s29, 0xa000
	global_load_lds_dwordx4 v[4:5], off
	v_lshl_add_u64 v[0:1], v[0:1], 0, s[4:5]
	s_mov_b32 m0, s59
	s_add_u32 s8, s44, 0x40080
	global_load_lds_dwordx4 v[0:1], off
	v_lshl_add_u64 v[0:1], v[2:3], 0, s[4:5]
	s_mov_b32 m0, s60
	s_addc_u32 s9, s45, 0
	global_load_lds_dwordx4 v[0:1], off
	s_add_i32 m0, s29, 0x1c000
	v_lshl_add_u64 v[0:1], s[8:9], 0, v[128:129]
	global_load_lds_dwordx4 v[0:1], off
	v_lshl_add_u64 v[0:1], s[8:9], 0, v[130:131]
	s_add_i32 m0, s29, 0x1e000
	s_cmpk_lt_u32 s6, 0x100
	global_load_lds_dwordx4 v[0:1], off
	s_waitcnt vmcnt(8)
	s_barrier
	v_bfe_u32 v1, v8, 4, 2
	v_and_b32_e32 v0, 15, v8
	v_lshlrev_b32_e32 v2, 4, v1
	v_lshl_or_b32 v142, s7, 6, v0
	v_lshl_or_b32 v0, v0, 6, v2
	v_lshlrev_b32_e32 v2, 2, v8
	v_and_b32_e32 v2, 32, v2
	v_bitop3_b32 v3, v0, s14, v2 bitop3:0xde
	v_bitop3_b32 v143, v0, s20, v2 bitop3:0xde
	v_lshlrev_b32_e32 v0, 14, v9
	v_and_b32_e32 v0, 0xffff8000, v0
	v_lshl_or_b32 v144, v1, 2, s15
	v_lshl_add_u32 v0, v10, 11, v0
	v_and_b32_e32 v1, 1, v9
	v_lshl_or_b32 v0, v1, 6, v0
	v_lshl_add_u32 v132, v11, 1, v0
	v_lshlrev_b32_e32 v0, 14, v12
	v_and_b32_e32 v0, 0xffff8000, v0
	s_waitcnt vmcnt(6)
	v_lshl_add_u32 v0, v13, 11, v0
	v_and_b32_e32 v1, 1, v12
	s_cselect_b64 s[6:7], -1, 0
	v_lshl_or_b32 v0, v1, 6, v0
	s_add_i32 s61, 0, 0x10000
	s_add_i32 s62, 0, 0x14000
	v_mov_b32_e32 v133, v129
	v_lshl_add_u32 v134, v14, 1, v0
	v_mov_b32_e32 v135, v129
	v_add_u32_e32 v145, s61, v143
	v_add_u32_e32 v146, s62, v143
	v_add_u32_e32 v147, 0, v3
	s_barrier
	s_branch .LBB0_198

; #define PG8_STAGE(bufoff, gbase, voff) do { _Pragma("unroll") for (int _i = 0; _i < 2; ++_i) \
;         __builtin_amdgcn_global_load_lds((const unsigned*)((const char*)(gbase) + (voff)[_i]), (LAS unsigned*)(lds + (bufoff) + ldsw + _i * 8192), 16, 0, 0); } while (0)
; #define PG8_WAIT_V(n) asm volatile("s_waitcnt vmcnt(" #n ")" ::: "memory")
; #define PG8_BAR __builtin_amdgcn_s_barrier()
; template <class Epi>
; __device__ __forceinline__ void gemm_phase(LAS unsigned char* lds, const Gemm g, const Sched& S, const Epi& E) {
;     ...
;     PG8_STAGE(PG8_SB(0, 0), cB, voffB); PG8_STAGE(PG8_SB(0, 1), cB + hstepB, voffB); PG8_STAGE(PG8_SA(0, 0), cA, voffA); PG8_STAGE(PG8_SA(0, 1), cA + hstepA, voffA);
;     if (wr == 1) PG8_BAR;
;     PG8_WAIT_V(2); PG8_BAR;
;     PG8_STAGE(PG8_SB(1, 0), cB + kstep, voffB); PG8_STAGE(PG8_SA(1, 0), cA + kstep, voffA); PG8_STAGE(PG8_SB(1, 1), cB + hstepB + kstep, voffB);
;     PG8_WAIT_V(6); PG8_BAR;
.LBB0_283:
	s_lshl_b32 s2, s2, 5
	s_and_b32 s22, s2, 0x60
	s_lshl_b32 s9, s8, 13
	s_lshl_b32 s23, s22, 7
	s_add_u32 s2, s34, 0x3700000
	s_mov_b64 s[4:5], 0x80
	s_addc_u32 s3, s35, 0
	s_add_i32 m0, s21, 0x18000
	v_lshl_add_u64 v[6:7], v[6:7], 0, s[4:5]
	global_load_lds_dwordx4 v[6:7], off
	v_lshl_add_u64 v[4:5], v[4:5], 0, s[4:5]
	s_add_i32 m0, s21, 0x1a000
	s_add_i32 s57, s21, 0x8000
	s_add_i32 s58, s21, 0xa000
	global_load_lds_dwordx4 v[4:5], off
	v_lshl_add_u64 v[0:1], v[0:1], 0, s[4:5]
	s_mov_b32 m0, s57
	s_add_u32 s14, s40, 0x40080
	global_load_lds_dwordx4 v[0:1], off
	v_lshl_add_u64 v[0:1], v[2:3], 0, s[4:5]
	s_mov_b32 m0, s58
	s_addc_u32 s15, s41, 0
	global_load_lds_dwordx4 v[0:1], off
	s_add_i32 m0, s21, 0x1c000
	v_lshl_add_u64 v[0:1], s[14:15], 0, v[130:131]
	global_load_lds_dwordx4 v[0:1], off
	v_lshl_add_u64 v[0:1], s[14:15], 0, v[134:135]
	s_add_i32 m0, s21, 0x1e000
	s_cmpk_lt_u32 s7, 0x100
	global_load_lds_dwordx4 v[0:1], off
	s_waitcnt vmcnt(8)
	s_barrier
	v_lshrrev_b32_e32 v1, 1, v8
	v_and_b32_e32 v1, 24, v1
	v_and_b32_e32 v0, 15, v8
	v_lshlrev_b32_e32 v2, 1, v1
	v_lshl_or_b32 v140, s8, 6, v0
	v_lshl_or_b32 v0, v0, 6, v2
	v_lshlrev_b32_e32 v2, 2, v8
	v_and_b32_e32 v2, 32, v2
	v_bitop3_b32 v3, v0, s9, v2 bitop3:0xde
	v_bitop3_b32 v141, v0, s23, v2 bitop3:0xde
	v_lshlrev_b32_e32 v0, 14, v9
	v_and_b32_e32 v0, 0xffff8000, v0
	v_or_b32_e32 v142, s22, v1
	v_lshl_add_u32 v0, v10, 11, v0
	v_and_b32_e32 v1, 1, v9
	v_lshl_or_b32 v0, v1, 6, v0
	v_lshl_add_u32 v136, v11, 1, v0
	v_lshlrev_b32_e32 v0, 14, v12
	v_and_b32_e32 v0, 0xffff8000, v0
	s_waitcnt vmcnt(6)
	v_lshl_add_u32 v0, v13, 11, v0
	v_and_b32_e32 v1, 1, v12
	s_sext_i32_i8 s61, s6
	s_cselect_b64 s[6:7], -1, 0
	v_lshl_or_b32 v0, v1, 6, v0
	s_add_i32 s59, 0, 0x10000
	s_add_i32 s60, 0, 0x14000
	v_mov_b32_e32 v137, v131
	v_lshl_add_u32 v138, v14, 1, v0
	v_mov_b32_e32 v139, v131
	v_add_u32_e32 v143, s59, v141
	v_add_u32_e32 v144, s60, v141
	v_add_u32_e32 v145, 0, v3
	s_barrier
	s_branch .LBB0_286

; #define PG8_STAGE(bufoff, gbase, voff) do { _Pragma("unroll") for (int _i = 0; _i < 2; ++_i) \
;         __builtin_amdgcn_global_load_lds((const unsigned*)((const char*)(gbase) + (voff)[_i]), (LAS unsigned*)(lds + (bufoff) + ldsw + _i * 8192), 16, 0, 0); } while (0)
; #define PG8_WAIT_V(n) asm volatile("s_waitcnt vmcnt(" #n ")" ::: "memory")
; #define PG8_BAR __builtin_amdgcn_s_barrier()
; template <class Epi>
; __device__ __forceinline__ void gemm_phase(LAS unsigned char* lds, const Gemm g, const Sched& S, const Epi& E) {
;     ...
;     f32x4 acc[2][2][4][2];
; #pragma unroll
;     for (int a = 0; a < 2; ++a)
; #pragma unroll
;         for (int b = 0; b < 2; ++b)
; #pragma unroll
;             for (int m = 0; m < 4; ++m)
; #pragma unroll
;                 for (int n = 0; n < 2; ++n) acc[a][b][m][n] = (f32x4){0.f, 0.f, 0.f, 0.f};
;     bf16x8 At[4][2], B0[2][2], B1[2][2];
;     const char* cA = (const char*)g.A + (size_t)S.aoff(cur) * 2; const char* cB = (const char*)g.Bt + (size_t)S.boff(cur) * 2;
;     PG8_STAGE(PG8_SB(0, 0), cB, voffB); PG8_STAGE(PG8_SB(0, 1), cB + hstepB, voffB); PG8_STAGE(PG8_SA(0, 0), cA, voffA); PG8_STAGE(PG8_SA(0, 1), cA + hstepA, voffA);
;     if (wr == 1) PG8_BAR;
;     PG8_WAIT_V(2); PG8_BAR;
;     PG8_STAGE(PG8_SB(1, 0), cB + kstep, voffB); PG8_STAGE(PG8_SA(1, 0), cA + kstep, voffA); PG8_STAGE(PG8_SB(1, 1), cB + hstepB + kstep, voffB);
;     PG8_WAIT_V(6); PG8_BAR;
.LBB0_362:
	s_mov_b64 s[8:9], 0x80
	s_and_b32 s47, s1, 3
	s_add_i32 m0, s57, 0x18000
	v_lshl_add_u64 v[6:7], v[6:7], 0, s[8:9]
	s_lshl_b32 s61, s46, 6
	s_lshl_b32 s3, s46, 13
	s_lshl_b32 s20, s47, 12
	global_load_lds_dwordx4 v[6:7], off
	v_lshl_add_u64 v[4:5], v[4:5], 0, s[8:9]
	s_add_i32 m0, s57, 0x1a000
	s_add_i32 s62, s57, 0x8000
	s_add_i32 s63, s57, 0xa000
	global_load_lds_dwordx4 v[4:5], off
	v_lshl_add_u64 v[0:1], v[0:1], 0, s[8:9]
	s_mov_b32 m0, s62
	s_add_u32 s14, s28, 0xb0080
	global_load_lds_dwordx4 v[0:1], off
	v_lshl_add_u64 v[0:1], v[2:3], 0, s[8:9]
	s_mov_b32 m0, s63
	s_addc_u32 s15, s29, 0
	global_load_lds_dwordx4 v[0:1], off
	s_add_i32 m0, s57, 0x1c000
	v_lshl_add_u64 v[0:1], s[14:15], 0, v[130:131]
	global_load_lds_dwordx4 v[0:1], off
	v_lshl_add_u64 v[0:1], s[14:15], 0, v[134:135]
	s_add_i32 m0, s57, 0x1e000
	v_and_b32_e32 v191, 15, v190
	global_load_lds_dwordx4 v[0:1], off
	s_waitcnt vmcnt(8)
	s_barrier
	v_and_b32_e32 v0, 48, v190
	v_lshlrev_b32_e32 v1, 2, v190
	v_lshl_or_b32 v0, v191, 6, v0
	v_and_b32_e32 v1, 32, v1
	v_bitop3_b32 v4, v0, s3, v1 bitop3:0xde
	v_bitop3_b32 v144, v0, s20, v1 bitop3:0xde
	v_lshrrev_b32_e32 v1, 1, v8
	v_mul_lo_u32 v0, v10, s2
	s_mov_b32 s3, 0xb000
	v_mad_u64_u32 v[0:1], s[22:23], v1, s3, v[0:1]
	v_or_b32_e32 v0, v0, v9
	s_mov_b64 s[20:21], 0xb0080
	v_add_lshl_u32 v0, v0, v11, 1
	v_mov_b32_e32 v1, v131
	v_lshl_add_u64 v[136:137], v[0:1], 0, s[20:21]
	v_lshrrev_b32_e32 v1, 1, v12
	v_mul_lo_u32 v0, v13, s2
	v_mad_u64_u32 v[0:1], s[2:3], v1, s3, v[0:1]
	v_or_b32_e32 v0, v0, v14
	s_waitcnt vmcnt(6)
	s_cmpk_lt_u32 s11, 0x100
	v_add_lshl_u32 v0, v0, v15, 1
	v_mov_b32_e32 v1, v131
	v_mov_b32_e32 v2, v131
	v_mov_b32_e32 v3, v131
	s_cselect_b64 s[14:15], -1, 0
	v_lshl_add_u64 v[138:139], v[0:1], 0, s[20:21]
	v_mov_b32_e32 v0, v131
	s_add_i32 s64, 0, 0x10000
	v_add_u32_e32 v145, 0, v4
	v_mov_b64_e32 v[6:7], v[2:3]
	v_mov_b64_e32 v[18:19], v[2:3]
	v_mov_b64_e32 v[22:23], v[2:3]
	v_mov_b64_e32 v[34:35], v[2:3]
	v_mov_b64_e32 v[38:39], v[2:3]
	v_mov_b64_e32 v[50:51], v[2:3]
	v_mov_b64_e32 v[54:55], v[2:3]
	v_mov_b64_e32 v[10:11], v[2:3]
	v_mov_b64_e32 v[14:15], v[2:3]
	v_mov_b64_e32 v[26:27], v[2:3]
	v_mov_b64_e32 v[30:31], v[2:3]
	v_mov_b64_e32 v[42:43], v[2:3]
	v_mov_b64_e32 v[46:47], v[2:3]
	v_mov_b64_e32 v[58:59], v[2:3]
	v_mov_b64_e32 v[62:63], v[2:3]
	v_mov_b64_e32 v[66:67], v[2:3]
	v_mov_b64_e32 v[70:71], v[2:3]
	v_mov_b64_e32 v[82:83], v[2:3]
	v_mov_b64_e32 v[86:87], v[2:3]
	v_mov_b64_e32 v[98:99], v[2:3]
	v_mov_b64_e32 v[102:103], v[2:3]
	v_mov_b64_e32 v[114:115], v[2:3]
	v_mov_b64_e32 v[118:119], v[2:3]
	v_mov_b64_e32 v[74:75], v[2:3]
	v_mov_b64_e32 v[78:79], v[2:3]
	v_mov_b64_e32 v[90:91], v[2:3]
	v_mov_b64_e32 v[94:95], v[2:3]
	v_mov_b64_e32 v[106:107], v[2:3]
	v_mov_b64_e32 v[110:111], v[2:3]
	v_mov_b64_e32 v[122:123], v[2:3]
	v_mov_b64_e32 v[126:127], v[2:3]
	s_sext_i32_i8 s0, s0
	v_or_b32_e32 v189, s61, v191
	s_mov_b32 s86, 0
	s_add_i32 s65, 0, 0x14000
	s_add_i32 s66, s57, 0xc000
	s_add_i32 s67, s57, 0xe000
	s_add_i32 s78, s64, s56
	v_mov_b64_e32 v[4:5], v[0:1]
	v_mov_b64_e32 v[16:17], v[0:1]
	v_mov_b64_e32 v[20:21], v[0:1]
	v_mov_b64_e32 v[32:33], v[0:1]
	v_mov_b64_e32 v[36:37], v[0:1]
	v_mov_b64_e32 v[48:49], v[0:1]
	v_mov_b64_e32 v[52:53], v[0:1]
	v_mov_b64_e32 v[8:9], v[0:1]
	v_mov_b64_e32 v[12:13], v[0:1]
	v_mov_b64_e32 v[24:25], v[0:1]
	v_mov_b64_e32 v[28:29], v[0:1]
	v_mov_b64_e32 v[40:41], v[0:1]
	v_mov_b64_e32 v[44:45], v[0:1]
	v_mov_b64_e32 v[56:57], v[0:1]
	v_mov_b64_e32 v[60:61], v[0:1]
	v_mov_b64_e32 v[64:65], v[0:1]
	v_mov_b64_e32 v[68:69], v[0:1]
	v_mov_b64_e32 v[80:81], v[0:1]
	v_mov_b64_e32 v[84:85], v[0:1]
	v_mov_b64_e32 v[96:97], v[0:1]
	v_mov_b64_e32 v[100:101], v[0:1]
	v_mov_b64_e32 v[112:113], v[0:1]
	v_mov_b64_e32 v[116:117], v[0:1]
	v_mov_b64_e32 v[72:73], v[0:1]
	v_mov_b64_e32 v[76:77], v[0:1]
	v_mov_b64_e32 v[88:89], v[0:1]
	v_mov_b64_e32 v[92:93], v[0:1]
	v_mov_b64_e32 v[104:105], v[0:1]
	v_mov_b64_e32 v[108:109], v[0:1]
	v_mov_b64_e32 v[120:121], v[0:1]
	v_mov_b64_e32 v[124:125], v[0:1]
	s_barrier

; #define PG8_STAGE(bufoff, gbase, voff) do { _Pragma("unroll") for (int _i = 0; _i < 2; ++_i) \
;         __builtin_amdgcn_global_load_lds((const unsigned*)((const char*)(gbase) + (voff)[_i]), (LAS unsigned*)(lds + (bufoff) + ldsw + _i * 8192), 16, 0, 0); } while (0)
; #define PG8_WAIT_V(n) asm volatile("s_waitcnt vmcnt(" #n ")" ::: "memory")
; #define PG8_BAR __builtin_amdgcn_s_barrier()
; template <class Epi>
; __device__ __forceinline__ void gemm_phase(LAS unsigned char* lds, const Gemm g, const Sched& S, const Epi& E) {
;     ...
;     PG8_STAGE(PG8_SB(0, 0), cB, voffB); PG8_STAGE(PG8_SB(0, 1), cB + hstepB, voffB); PG8_STAGE(PG8_SA(0, 0), cA, voffA); PG8_STAGE(PG8_SA(0, 1), cA + hstepA, voffA);
;     if (wr == 1) PG8_BAR;
;     PG8_WAIT_V(2); PG8_BAR;
;     PG8_STAGE(PG8_SB(1, 0), cB + kstep, voffB); PG8_STAGE(PG8_SA(1, 0), cA + kstep, voffA); PG8_STAGE(PG8_SB(1, 1), cB + hstepB + kstep, voffB);
;     PG8_WAIT_V(6); PG8_BAR;
.LBB0_510:
	s_add_u32 s8, s34, 0x12800000
	s_addc_u32 s9, s35, 0
	s_lshl_b32 s14, s14, 5
	s_and_b32 s24, s14, 0x60
	s_mov_b64 s[14:15], 0x80
	s_add_i32 m0, s10, 0x18000
	v_lshl_add_u64 v[6:7], v[6:7], 0, s[14:15]
	s_lshl_b32 s21, s0, 13
	s_lshl_b32 s25, s24, 7
	global_load_lds_dwordx4 v[6:7], off
	v_lshl_add_u64 v[4:5], v[4:5], 0, s[14:15]
	s_add_i32 m0, s10, 0x1a000
	s_add_i32 s87, s10, 0x8000
	s_add_i32 s88, s10, 0xa000
	global_load_lds_dwordx4 v[4:5], off
	v_lshl_add_u64 v[0:1], v[0:1], 0, s[14:15]
	s_mov_b32 m0, s87
	s_add_u32 s22, s4, 0x40080
	global_load_lds_dwordx4 v[0:1], off
	v_lshl_add_u64 v[0:1], v[2:3], 0, s[14:15]
	s_mov_b32 m0, s88
	s_addc_u32 s23, s5, 0
	global_load_lds_dwordx4 v[0:1], off
	s_add_i32 m0, s10, 0x1c000
	v_lshl_add_u64 v[0:1], s[22:23], 0, v[138:139]
	global_load_lds_dwordx4 v[0:1], off
	v_lshl_add_u64 v[0:1], s[22:23], 0, v[142:143]
	s_add_i32 m0, s10, 0x1e000
	s_cmpk_lt_u32 s20, 0x100
	global_load_lds_dwordx4 v[0:1], off
	s_waitcnt vmcnt(8)
	s_barrier
	v_lshrrev_b32_e32 v1, 1, v8
	v_and_b32_e32 v1, 24, v1
	v_and_b32_e32 v0, 15, v8
	v_lshlrev_b32_e32 v2, 1, v1
	v_lshl_or_b32 v157, s0, 6, v0
	v_lshl_or_b32 v0, v0, 6, v2
	v_lshlrev_b32_e32 v2, 2, v8
	v_and_b32_e32 v2, 32, v2
	v_bitop3_b32 v3, v0, s21, v2 bitop3:0xde
	v_bitop3_b32 v158, v0, s25, v2 bitop3:0xde
	v_or_b32_e32 v0, s24, v1
	v_lshlrev_b32_e32 v1, 14, v9
	v_and_b32_e32 v1, 0xffff8000, v1
	v_lshl_add_u32 v1, v10, 11, v1
	v_and_b32_e32 v2, 1, v9
	v_lshl_or_b32 v1, v2, 6, v1
	v_lshl_add_u32 v146, v11, 1, v1
	v_lshlrev_b32_e32 v1, 14, v12
	v_and_b32_e32 v1, 0xffff8000, v1
	s_waitcnt vmcnt(6)
	v_lshl_add_u32 v1, v13, 11, v1
	v_and_b32_e32 v2, 1, v12
	s_cselect_b64 s[20:21], -1, 0
	v_lshl_or_b32 v1, v2, 6, v1
	s_add_i32 s89, 0, 0x10000
	s_add_i32 s90, 0, 0x14000
	v_or_b32_e32 v159, 0xfffff780, v0
	v_mov_b32_e32 v147, v145
	v_lshl_add_u32 v148, v14, 1, v1
	v_mov_b32_e32 v149, v145
	v_add_u32_e32 v160, s89, v158
	v_add_u32_e32 v161, s90, v158
	v_add_u32_e32 v162, 0, v3
	v_lshlrev_b32_e32 v150, 1, v0
	s_movk_i32 s91, 0x4080
	s_mov_b32 s92, 0
	s_barrier
	s_branch .LBB0_513

; #define PG8_STAGE(bufoff, gbase, voff) do { _Pragma("unroll") for (int _i = 0; _i < 2; ++_i) \
;         __builtin_amdgcn_global_load_lds((const unsigned*)((const char*)(gbase) + (voff)[_i]), (LAS unsigned*)(lds + (bufoff) + ldsw + _i * 8192), 16, 0, 0); } while (0)
; #define PG8_WAIT_V(n) asm volatile("s_waitcnt vmcnt(" #n ")" ::: "memory")
; #define PG8_BAR __builtin_amdgcn_s_barrier()
; template <class Epi>
; __device__ __forceinline__ void gemm_phase(LAS unsigned char* lds, const Gemm g, const Sched& S, const Epi& E) {
;     ...
;     PG8_STAGE(PG8_SB(0, 0), cB, voffB); PG8_STAGE(PG8_SB(0, 1), cB + hstepB, voffB); PG8_STAGE(PG8_SA(0, 0), cA, voffA); PG8_STAGE(PG8_SA(0, 1), cA + hstepA, voffA);
;     if (wr == 1) PG8_BAR;
;     PG8_WAIT_V(2); PG8_BAR;
;     PG8_STAGE(PG8_SB(1, 0), cB + kstep, voffB); PG8_STAGE(PG8_SA(1, 0), cA + kstep, voffA); PG8_STAGE(PG8_SB(1, 1), cB + hstepB + kstep, voffB);
;     PG8_WAIT_V(6); PG8_BAR;
.LBB0_767:
	s_lshl_b32 s5, s6, 5
	s_mov_b64 s[6:7], 0x80
	s_and_b32 s5, s5, 0x60
	s_add_i32 m0, s10, 0x18000
	v_lshl_add_u64 v[6:7], v[6:7], 0, s[6:7]
	s_lshl_b32 s3, s9, 13
	s_lshl_b32 s11, s5, 7
	global_load_lds_dwordx4 v[6:7], off
	v_lshl_add_u64 v[4:5], v[4:5], 0, s[6:7]
	s_add_i32 m0, s10, 0x1a000
	s_add_i32 s94, s10, 0x8000
	s_add_i32 s95, s10, 0xa000
	global_load_lds_dwordx4 v[4:5], off
	v_lshl_add_u64 v[0:1], v[0:1], 0, s[6:7]
	s_mov_b32 m0, s94
	s_add_u32 s24, s52, 0x10080
	global_load_lds_dwordx4 v[0:1], off
	v_lshl_add_u64 v[0:1], v[2:3], 0, s[6:7]
	s_mov_b32 m0, s95
	s_addc_u32 s25, s53, 0
	global_load_lds_dwordx4 v[0:1], off
	s_add_i32 m0, s10, 0x1c000
	v_lshl_add_u64 v[0:1], s[24:25], 0, v[146:147]
	global_load_lds_dwordx4 v[0:1], off
	v_lshl_add_u64 v[0:1], s[24:25], 0, v[150:151]
	s_add_i32 m0, s10, 0x1e000
	s_cmpk_lt_u32 s8, 0x100
	global_load_lds_dwordx4 v[0:1], off
	s_waitcnt vmcnt(8)
	s_barrier
	v_lshrrev_b32_e32 v1, 1, v8
	v_and_b32_e32 v1, 24, v1
	v_and_b32_e32 v0, 15, v8
	v_lshlrev_b32_e32 v2, 1, v1
	v_lshl_or_b32 v159, s9, 6, v0
	v_lshl_or_b32 v0, v0, 6, v2
	v_lshlrev_b32_e32 v2, 2, v8
	v_and_b32_e32 v2, 32, v2
	s_waitcnt vmcnt(6)
	v_bitop3_b32 v3, v0, s3, v2 bitop3:0xde
	v_bitop3_b32 v160, v0, s11, v2 bitop3:0xde
	s_cselect_b64 s[8:9], -1, 0
	s_add_i32 s96, 0, 0x10000
	s_add_i32 s97, 0, 0x14000
	v_or_b32_e32 v161, s5, v1
	v_add_u32_e32 v162, s96, v160
	v_add_u32_e32 v163, s97, v160
	v_add_u32_e32 v164, 0, v3
	s_mov_b32 s14, 0x3f1b4598
	s_add_i32 s88, s10, 0xc000
	s_add_i32 s11, s10, 0xe000
	s_barrier
	s_branch .LBB0_770

; #define PG8_STAGE(bufoff, gbase, voff) do { _Pragma("unroll") for (int _i = 0; _i < 2; ++_i) \
;         __builtin_amdgcn_global_load_lds((const unsigned*)((const char*)(gbase) + (voff)[_i]), (LAS unsigned*)(lds + (bufoff) + ldsw + _i * 8192), 16, 0, 0); } while (0)
; #define PG8_WAIT_V(n) asm volatile("s_waitcnt vmcnt(" #n ")" ::: "memory")
; #define PG8_BAR __builtin_amdgcn_s_barrier()
; template <class Epi>
; __device__ __forceinline__ void gemm_phase(LAS unsigned char* lds, const Gemm g, const Sched& S, const Epi& E) {
;     ...
;     PG8_STAGE(PG8_SB(0, 0), cB, voffB); PG8_STAGE(PG8_SB(0, 1), cB + hstepB, voffB); PG8_STAGE(PG8_SA(0, 0), cA, voffA); PG8_STAGE(PG8_SA(0, 1), cA + hstepA, voffA);
;     if (wr == 1) PG8_BAR;
;     PG8_WAIT_V(2); PG8_BAR;
;     PG8_STAGE(PG8_SB(1, 0), cB + kstep, voffB); PG8_STAGE(PG8_SA(1, 0), cA + kstep, voffA); PG8_STAGE(PG8_SB(1, 1), cB + hstepB + kstep, voffB);
;     PG8_WAIT_V(6); PG8_BAR;
.LBB0_888:
	s_lshl_b32 s8, s8, 5
	s_mov_b64 s[46:47], 0x80
	s_and_b32 s14, s8, 0x60
	s_add_i32 m0, s11, 0x18000
	v_lshl_add_u64 v[6:7], v[6:7], 0, s[46:47]
	s_lshl_b32 s1, s3, 13
	s_lshl_b32 s15, s14, 7
	global_load_lds_dwordx4 v[6:7], off
	v_lshl_add_u64 v[4:5], v[4:5], 0, s[46:47]
	s_add_i32 m0, s11, 0x1a000
	s_add_i32 s97, s11, 0x8000
	s_add_i32 s58, s11, 0xa000
	global_load_lds_dwordx4 v[4:5], off
	v_lshl_add_u64 v[0:1], v[0:1], 0, s[46:47]
	s_mov_b32 m0, s97
	s_add_u32 s8, s6, 0x10080
	global_load_lds_dwordx4 v[0:1], off
	v_lshl_add_u64 v[0:1], v[2:3], 0, s[46:47]
	s_mov_b32 m0, s58
	s_addc_u32 s9, s7, 0
	global_load_lds_dwordx4 v[0:1], off
	s_add_i32 m0, s11, 0x1c000
	v_lshl_add_u64 v[0:1], s[8:9], 0, v[138:139]
	global_load_lds_dwordx4 v[0:1], off
	v_lshl_add_u64 v[0:1], s[8:9], 0, v[142:143]
	s_add_i32 m0, s11, 0x1e000
	s_cmpk_lt_u32 s2, 0x100
	global_load_lds_dwordx4 v[0:1], off
	s_waitcnt vmcnt(8)
	s_barrier
	v_lshrrev_b32_e32 v1, 1, v8
	v_and_b32_e32 v1, 24, v1
	v_and_b32_e32 v0, 15, v8
	v_lshlrev_b32_e32 v2, 1, v1
	v_lshl_or_b32 v152, s3, 6, v0
	v_lshl_or_b32 v0, v0, 6, v2
	v_lshlrev_b32_e32 v2, 2, v8
	v_and_b32_e32 v2, 32, v2
	s_waitcnt vmcnt(6)
	v_bitop3_b32 v3, v0, s1, v2 bitop3:0xde
	v_bitop3_b32 v153, v0, s15, v2 bitop3:0xde
	s_cselect_b64 s[52:53], -1, 0
	s_add_i32 s59, 0, 0x10000
	s_add_i32 s60, 0, 0x14000
	v_or_b32_e32 v154, s14, v1
	v_add_u32_e32 v155, s59, v153
	v_add_u32_e32 v156, s60, v153
	v_add_u32_e32 v157, 0, v3
	s_barrier
	s_branch .LBB0_891

; #define PG8_STAGE(bufoff, gbase, voff) do { _Pragma("unroll") for (int _i = 0; _i < 2; ++_i) \
;         __builtin_amdgcn_global_load_lds((const unsigned*)((const char*)(gbase) + (voff)[_i]), (LAS unsigned*)(lds + (bufoff) + ldsw + _i * 8192), 16, 0, 0); } while (0)
; #define PG8_WAIT_V(n) asm volatile("s_waitcnt vmcnt(" #n ")" ::: "memory")
; #define PG8_BAR __builtin_amdgcn_s_barrier()
; template <class Epi>
; __device__ __forceinline__ void gemm_phase(LAS unsigned char* lds, const Gemm g, const Sched& S, const Epi& E) {
;     ...
;     f32x4 acc[2][2][4][2];
; #pragma unroll
;     for (int a = 0; a < 2; ++a)
; #pragma unroll
;         for (int b = 0; b < 2; ++b)
; #pragma unroll
;             for (int m = 0; m < 4; ++m)
; #pragma unroll
;                 for (int n = 0; n < 2; ++n) acc[a][b][m][n] = (f32x4){0.f, 0.f, 0.f, 0.f};
;     bf16x8 At[4][2], B0[2][2], B1[2][2];
;     const char* cA = (const char*)g.A + (size_t)S.aoff(cur) * 2; const char* cB = (const char*)g.Bt + (size_t)S.boff(cur) * 2;
;     PG8_STAGE(PG8_SB(0, 0), cB, voffB); PG8_STAGE(PG8_SB(0, 1), cB + hstepB, voffB); PG8_STAGE(PG8_SA(0, 0), cA, voffA); PG8_STAGE(PG8_SA(0, 1), cA + hstepA, voffA);
;     if (wr == 1) PG8_BAR;
;     PG8_WAIT_V(2); PG8_BAR;
;     PG8_STAGE(PG8_SB(1, 0), cB + kstep, voffB); PG8_STAGE(PG8_SA(1, 0), cA + kstep, voffA); PG8_STAGE(PG8_SB(1, 1), cB + hstepB + kstep, voffB);
;     PG8_WAIT_V(6); PG8_BAR;
.LBB0_1206:
	s_mov_b64 s[4:5], 0x80
	s_and_b32 s21, s1, 3
	s_add_i32 m0, s51, 0x18000
	v_lshl_add_u64 v[6:7], v[6:7], 0, s[4:5]
	s_lshl_b32 s55, s13, 6
	s_lshl_b32 s24, s13, 13
	s_lshl_b32 s25, s21, 12
	global_load_lds_dwordx4 v[6:7], off
	v_lshl_add_u64 v[4:5], v[4:5], 0, s[4:5]
	s_add_i32 m0, s51, 0x1a000
	s_add_i32 s56, s51, 0x8000
	s_add_i32 s57, s51, 0xa000
	global_load_lds_dwordx4 v[4:5], off
	v_lshl_add_u64 v[0:1], v[0:1], 0, s[4:5]
	s_mov_b32 m0, s56
	s_add_u32 s22, s44, 0x40080
	global_load_lds_dwordx4 v[0:1], off
	v_lshl_add_u64 v[0:1], v[2:3], 0, s[4:5]
	s_mov_b32 m0, s57
	s_addc_u32 s23, s45, 0
	global_load_lds_dwordx4 v[0:1], off
	s_add_i32 m0, s51, 0x1c000
	v_lshl_add_u64 v[0:1], s[22:23], 0, v[130:131]
	global_load_lds_dwordx4 v[0:1], off
	v_lshl_add_u64 v[0:1], s[22:23], 0, v[134:135]
	s_add_i32 m0, s51, 0x1e000
	v_and_b32_e32 v191, 15, v190
	global_load_lds_dwordx4 v[0:1], off
	s_waitcnt vmcnt(8)
	s_barrier
	v_and_b32_e32 v0, 48, v190
	v_lshlrev_b32_e32 v1, 2, v190
	v_lshl_or_b32 v0, v191, 6, v0
	v_and_b32_e32 v1, 32, v1
	v_bitop3_b32 v4, v0, s24, v1 bitop3:0xde
	v_bitop3_b32 v144, v0, s25, v1 bitop3:0xde
	v_lshlrev_b32_e32 v0, 14, v8
	v_and_b32_e32 v0, 0xffff8000, v0
	v_lshl_add_u32 v0, v9, 11, v0
	v_and_b32_e32 v1, 1, v8
	v_lshl_or_b32 v0, v1, 6, v0
	s_mov_b64 s[24:25], 0x40080
	v_lshl_add_u32 v0, v10, 1, v0
	v_mov_b32_e32 v1, v131
	v_lshl_add_u64 v[136:137], v[0:1], 0, s[24:25]
	v_lshlrev_b32_e32 v0, 14, v11
	v_and_b32_e32 v0, 0xffff8000, v0
	v_lshl_add_u32 v0, v12, 11, v0
	v_and_b32_e32 v1, 1, v11
	v_lshl_or_b32 v0, v1, 6, v0
	s_waitcnt vmcnt(6)
	v_lshl_add_u32 v0, v13, 1, v0
	v_mov_b32_e32 v1, v131
	v_mov_b32_e32 v2, v131
	v_mov_b32_e32 v3, v131
	s_cmpk_lt_u32 s11, 0x100
	v_lshl_add_u64 v[138:139], v[0:1], 0, s[24:25]
	v_mov_b32_e32 v0, v131
	v_add_u32_e32 v145, 0, v4
	v_mov_b64_e32 v[6:7], v[2:3]
	v_mov_b64_e32 v[18:19], v[2:3]
	v_mov_b64_e32 v[22:23], v[2:3]
	v_mov_b64_e32 v[34:35], v[2:3]
	v_mov_b64_e32 v[38:39], v[2:3]
	v_mov_b64_e32 v[50:51], v[2:3]
	v_mov_b64_e32 v[54:55], v[2:3]
	v_mov_b64_e32 v[10:11], v[2:3]
	v_mov_b64_e32 v[14:15], v[2:3]
	v_mov_b64_e32 v[26:27], v[2:3]
	v_mov_b64_e32 v[30:31], v[2:3]
	v_mov_b64_e32 v[42:43], v[2:3]
	v_mov_b64_e32 v[46:47], v[2:3]
	v_mov_b64_e32 v[58:59], v[2:3]
	v_mov_b64_e32 v[62:63], v[2:3]
	v_mov_b64_e32 v[66:67], v[2:3]
	v_mov_b64_e32 v[70:71], v[2:3]
	v_mov_b64_e32 v[82:83], v[2:3]
	v_mov_b64_e32 v[86:87], v[2:3]
	v_mov_b64_e32 v[98:99], v[2:3]
	v_mov_b64_e32 v[102:103], v[2:3]
	v_mov_b64_e32 v[114:115], v[2:3]
	v_mov_b64_e32 v[118:119], v[2:3]
	v_mov_b64_e32 v[74:75], v[2:3]
	v_mov_b64_e32 v[78:79], v[2:3]
	v_mov_b64_e32 v[90:91], v[2:3]
	v_mov_b64_e32 v[94:95], v[2:3]
	v_mov_b64_e32 v[106:107], v[2:3]
	v_mov_b64_e32 v[110:111], v[2:3]
	v_mov_b64_e32 v[122:123], v[2:3]
	v_mov_b64_e32 v[126:127], v[2:3]
	s_sext_i32_i8 s0, s0
	v_or_b32_e32 v189, s55, v191
	s_cselect_b64 s[22:23], -1, 0
	s_mov_b32 s61, 0
	s_add_i32 s58, 0, 0x10000
	s_add_i32 s59, 0, 0x14000
	v_mov_b64_e32 v[4:5], v[0:1]
	v_mov_b64_e32 v[16:17], v[0:1]
	v_mov_b64_e32 v[20:21], v[0:1]
	v_mov_b64_e32 v[32:33], v[0:1]
	v_mov_b64_e32 v[36:37], v[0:1]
	v_mov_b64_e32 v[48:49], v[0:1]
	v_mov_b64_e32 v[52:53], v[0:1]
	v_mov_b64_e32 v[8:9], v[0:1]
	v_mov_b64_e32 v[12:13], v[0:1]
	v_mov_b64_e32 v[24:25], v[0:1]
	v_mov_b64_e32 v[28:29], v[0:1]
	v_mov_b64_e32 v[40:41], v[0:1]
	v_mov_b64_e32 v[44:45], v[0:1]
	v_mov_b64_e32 v[56:57], v[0:1]
	v_mov_b64_e32 v[60:61], v[0:1]
	v_mov_b64_e32 v[64:65], v[0:1]
	v_mov_b64_e32 v[68:69], v[0:1]
	v_mov_b64_e32 v[80:81], v[0:1]
	v_mov_b64_e32 v[84:85], v[0:1]
	v_mov_b64_e32 v[96:97], v[0:1]
	v_mov_b64_e32 v[100:101], v[0:1]
	v_mov_b64_e32 v[112:113], v[0:1]
	v_mov_b64_e32 v[116:117], v[0:1]
	v_mov_b64_e32 v[72:73], v[0:1]
	v_mov_b64_e32 v[76:77], v[0:1]
	v_mov_b64_e32 v[88:89], v[0:1]
	v_mov_b64_e32 v[92:93], v[0:1]
	v_mov_b64_e32 v[104:105], v[0:1]
	v_mov_b64_e32 v[108:109], v[0:1]
	v_mov_b64_e32 v[120:121], v[0:1]
	v_mov_b64_e32 v[124:125], v[0:1]
	s_barrier

; #define PG8_STAGE(bufoff, gbase, voff) do { _Pragma("unroll") for (int _i = 0; _i < 2; ++_i) \
;         __builtin_amdgcn_global_load_lds((const unsigned*)((const char*)(gbase) + (voff)[_i]), (LAS unsigned*)(lds + (bufoff) + ldsw + _i * 8192), 16, 0, 0); } while (0)
; #define PG8_WAIT_V(n) asm volatile("s_waitcnt vmcnt(" #n ")" ::: "memory")
; #define PG8_BAR __builtin_amdgcn_s_barrier()
; template <class Epi>
; __device__ __forceinline__ void gemm_phase(LAS unsigned char* lds, const Gemm g, const Sched& S, const Epi& E) {
;     ...
;     PG8_STAGE(PG8_SB(0, 0), cB, voffB); PG8_STAGE(PG8_SB(0, 1), cB + hstepB, voffB); PG8_STAGE(PG8_SA(0, 0), cA, voffA); PG8_STAGE(PG8_SA(0, 1), cA + hstepA, voffA);
;     if (wr == 1) PG8_BAR;
;     PG8_WAIT_V(2); PG8_BAR;
;     PG8_STAGE(PG8_SB(1, 0), cB + kstep, voffB); PG8_STAGE(PG8_SA(1, 0), cA + kstep, voffA); PG8_STAGE(PG8_SB(1, 1), cB + hstepB + kstep, voffB);
;     PG8_WAIT_V(6); PG8_BAR;
.LBB0_1345:
	s_lshl_b32 s14, s14, 5
	s_and_b32 s23, s14, 0x60
	s_mov_b64 s[14:15], 0x80
	s_add_i32 m0, s11, 0x18000
	v_lshl_add_u64 v[6:7], v[6:7], 0, s[14:15]
	s_lshl_b32 s22, s18, 13
	s_lshl_b32 s24, s23, 7
	global_load_lds_dwordx4 v[6:7], off
	v_lshl_add_u64 v[4:5], v[4:5], 0, s[14:15]
	s_add_i32 m0, s11, 0x1a000
	s_add_i32 s45, s11, 0x8000
	s_add_i32 s46, s11, 0xa000
	global_load_lds_dwordx4 v[4:5], off
	v_lshl_add_u64 v[0:1], v[0:1], 0, s[14:15]
	s_mov_b32 m0, s45
	s_add_u32 s20, s40, 0x40080
	global_load_lds_dwordx4 v[0:1], off
	v_lshl_add_u64 v[0:1], v[2:3], 0, s[14:15]
	s_mov_b32 m0, s46
	s_addc_u32 s21, s41, 0
	global_load_lds_dwordx4 v[0:1], off
	s_add_i32 m0, s11, 0x1c000
	v_lshl_add_u64 v[0:1], s[20:21], 0, v[130:131]
	global_load_lds_dwordx4 v[0:1], off
	v_lshl_add_u64 v[0:1], s[20:21], 0, v[134:135]
	s_add_i32 m0, s11, 0x1e000
	s_cmpk_lt_u32 s17, 0x100
	global_load_lds_dwordx4 v[0:1], off
	s_waitcnt vmcnt(8)
	s_barrier
	v_lshrrev_b32_e32 v1, 1, v8
	v_and_b32_e32 v1, 24, v1
	v_and_b32_e32 v0, 15, v8
	v_lshlrev_b32_e32 v2, 1, v1
	v_lshl_or_b32 v145, s18, 6, v0
	v_lshl_or_b32 v0, v0, 6, v2
	v_lshlrev_b32_e32 v2, 2, v8
	v_and_b32_e32 v2, 32, v2
	v_bitop3_b32 v3, v0, s22, v2 bitop3:0xde
	v_bitop3_b32 v146, v0, s24, v2 bitop3:0xde
	v_lshlrev_b32_e32 v0, 14, v9
	v_and_b32_e32 v0, 0xffff8000, v0
	v_or_b32_e32 v147, s23, v1
	v_lshl_add_u32 v0, v10, 11, v0
	v_and_b32_e32 v1, 1, v9
	v_lshl_or_b32 v0, v1, 6, v0
	v_lshl_add_u32 v136, v11, 1, v0
	v_lshlrev_b32_e32 v0, 14, v12
	v_and_b32_e32 v0, 0xffff8000, v0
	s_waitcnt vmcnt(6)
	v_lshl_add_u32 v0, v13, 11, v0
	v_and_b32_e32 v1, 1, v12
	s_sext_i32_i8 s49, s16
	s_cselect_b64 s[16:17], -1, 0
	v_lshl_or_b32 v0, v1, 6, v0
	s_add_i32 s47, 0, 0x10000
	s_add_i32 s48, 0, 0x14000
	v_mov_b32_e32 v137, v131
	v_lshl_add_u32 v138, v14, 1, v0
	v_mov_b32_e32 v139, v131
	v_add_u32_e32 v148, s47, v146
	v_add_u32_e32 v149, s48, v146
	v_add_u32_e32 v150, 0, v3
	s_mov_b32 s18, 0x3db8aa3b
	s_barrier
	s_branch .LBB0_1348

; #define PG8_STAGE(bufoff, gbase, voff) do { _Pragma("unroll") for (int _i = 0; _i < 2; ++_i) \
;         __builtin_amdgcn_global_load_lds((const unsigned*)((const char*)(gbase) + (voff)[_i]), (LAS unsigned*)(lds + (bufoff) + ldsw + _i * 8192), 16, 0, 0); } while (0)
; #define PG8_WAIT_V(n) asm volatile("s_waitcnt vmcnt(" #n ")" ::: "memory")
; #define PG8_BAR __builtin_amdgcn_s_barrier()
; template <class Epi>
; __device__ __forceinline__ void gemm_phase(LAS unsigned char* lds, const Gemm g, const Sched& S, const Epi& E) {
;     ...
;     f32x4 acc[2][2][4][2];
; #pragma unroll
;     for (int a = 0; a < 2; ++a)
; #pragma unroll
;         for (int b = 0; b < 2; ++b)
; #pragma unroll
;             for (int m = 0; m < 4; ++m)
; #pragma unroll
;                 for (int n = 0; n < 2; ++n) acc[a][b][m][n] = (f32x4){0.f, 0.f, 0.f, 0.f};
;     bf16x8 At[4][2], B0[2][2], B1[2][2];
;     const char* cA = (const char*)g.A + (size_t)S.aoff(cur) * 2; const char* cB = (const char*)g.Bt + (size_t)S.boff(cur) * 2;
;     PG8_STAGE(PG8_SB(0, 0), cB, voffB); PG8_STAGE(PG8_SB(0, 1), cB + hstepB, voffB); PG8_STAGE(PG8_SA(0, 0), cA, voffA); PG8_STAGE(PG8_SA(0, 1), cA + hstepA, voffA);
;     if (wr == 1) PG8_BAR;
;     PG8_WAIT_V(2); PG8_BAR;
;     PG8_STAGE(PG8_SB(1, 0), cB + kstep, voffB); PG8_STAGE(PG8_SA(1, 0), cA + kstep, voffA); PG8_STAGE(PG8_SB(1, 1), cB + hstepB + kstep, voffB);
;     PG8_WAIT_V(6); PG8_BAR;
.LBB0_1369:
	v_and_b32_e32 v139, 15, v8
	v_bfe_u32 v137, v8, 4, 2
	v_lshlrev_b32_e32 v8, 4, v137
	v_lshlrev_b32_e32 v138, 2, v139
	s_mov_b64 s[24:25], 0x80
	s_and_b32 s11, s4, 3
	v_lshl_or_b32 v8, v139, 6, v8
	s_lshl_b32 s4, s56, 13
	v_and_b32_e32 v9, 32, v138
	s_add_i32 m0, s17, 0x18000
	v_lshl_add_u64 v[6:7], v[6:7], 0, s[24:25]
	v_bitop3_b32 v10, v8, s4, v9 bitop3:0xde
	s_lshl_b32 s4, s11, 12
	global_load_lds_dwordx4 v[6:7], off
	v_lshl_add_u64 v[4:5], v[4:5], 0, s[24:25]
	s_add_i32 m0, s17, 0x1a000
	s_add_i32 s64, s17, 0x8000
	s_add_i32 s65, s17, 0xa000
	v_bitop3_b32 v140, v8, s4, v9 bitop3:0xde
	global_load_lds_dwordx4 v[4:5], off
	v_lshl_add_u64 v[0:1], v[0:1], 0, s[24:25]
	s_mov_b32 m0, s64
	s_add_u32 s4, s20, 0x40080
	global_load_lds_dwordx4 v[0:1], off
	v_lshl_add_u64 v[0:1], v[2:3], 0, s[24:25]
	s_mov_b32 m0, s65
	s_addc_u32 s5, s21, 0
	global_load_lds_dwordx4 v[0:1], off
	s_add_i32 m0, s17, 0x1c000
	v_lshl_add_u64 v[0:1], s[4:5], 0, v[130:131]
	global_load_lds_dwordx4 v[0:1], off
	v_lshl_add_u64 v[0:1], s[4:5], 0, v[134:135]
	s_add_i32 m0, s17, 0x1e000
	s_cmpk_lt_u32 s13, 0x100
	global_load_lds_dwordx4 v[0:1], off
	s_waitcnt vmcnt(8)
	s_barrier
	s_waitcnt vmcnt(6)
	v_lshl_or_b32 v136, s56, 6, v139
	s_cselect_b64 s[26:27], -1, 0
	s_add_i32 s66, 0, 0x10000
	s_add_i32 s67, 0, 0x14000
	v_add_u32_e32 v141, 0, v10
	v_mov_b32_e32 v0, v131
	v_mov_b32_e32 v1, v131
	v_mov_b32_e32 v2, v131
	v_mov_b32_e32 v3, v131
	v_mov_b32_e32 v4, v131
	v_mov_b32_e32 v5, v131
	v_mov_b32_e32 v6, v131
	v_mov_b32_e32 v7, v131
	v_mov_b32_e32 v8, v131
	v_mov_b32_e32 v9, v131
	v_mov_b32_e32 v10, v131
	v_mov_b32_e32 v11, v131
	v_mov_b32_e32 v16, v131
	v_mov_b32_e32 v17, v131
	v_mov_b32_e32 v18, v131
	v_mov_b32_e32 v19, v131
	v_mov_b32_e32 v24, v131
	v_mov_b32_e32 v25, v131
	v_mov_b32_e32 v26, v131
	v_mov_b32_e32 v27, v131
	v_mov_b32_e32 v32, v131
	v_mov_b32_e32 v33, v131
	v_mov_b32_e32 v34, v131
	v_mov_b32_e32 v35, v131
	v_mov_b32_e32 v40, v131
	v_mov_b32_e32 v41, v131
	v_mov_b32_e32 v42, v131
	v_mov_b32_e32 v43, v131
	v_mov_b32_e32 v48, v131
	v_mov_b32_e32 v49, v131
	v_mov_b32_e32 v50, v131
	v_mov_b32_e32 v51, v131
	v_mov_b32_e32 v12, v131
	v_mov_b32_e32 v13, v131
	v_mov_b32_e32 v14, v131
	v_mov_b32_e32 v15, v131
	v_mov_b32_e32 v20, v131
	v_mov_b32_e32 v21, v131
	v_mov_b32_e32 v22, v131
	v_mov_b32_e32 v23, v131
	v_mov_b32_e32 v28, v131
	v_mov_b32_e32 v29, v131
	v_mov_b32_e32 v30, v131
	v_mov_b32_e32 v31, v131
	v_mov_b32_e32 v36, v131
	v_mov_b32_e32 v37, v131
	v_mov_b32_e32 v38, v131
	v_mov_b32_e32 v39, v131
	v_mov_b32_e32 v44, v131
	v_mov_b32_e32 v45, v131
	v_mov_b32_e32 v46, v131
	v_mov_b32_e32 v47, v131
	v_mov_b32_e32 v52, v131
	v_mov_b32_e32 v53, v131
	v_mov_b32_e32 v54, v131
	v_mov_b32_e32 v55, v131
	v_mov_b32_e32 v56, v131
	v_mov_b32_e32 v57, v131
	v_mov_b32_e32 v58, v131
	v_mov_b32_e32 v59, v131
	v_mov_b32_e32 v60, v131
	v_mov_b32_e32 v61, v131
	v_mov_b32_e32 v62, v131
	v_mov_b32_e32 v63, v131
	v_mov_b32_e32 v64, v131
	v_mov_b32_e32 v65, v131
	v_mov_b32_e32 v66, v131
	v_mov_b32_e32 v67, v131
	v_mov_b32_e32 v68, v131
	v_mov_b32_e32 v69, v131
	v_mov_b32_e32 v70, v131
	v_mov_b32_e32 v71, v131
	v_mov_b32_e32 v72, v131
	v_mov_b32_e32 v73, v131
	v_mov_b32_e32 v74, v131
	v_mov_b32_e32 v75, v131
	v_mov_b32_e32 v80, v131
	v_mov_b32_e32 v81, v131
	v_mov_b32_e32 v82, v131
	v_mov_b32_e32 v83, v131
	v_mov_b32_e32 v88, v131
	v_mov_b32_e32 v89, v131
	v_mov_b32_e32 v90, v131
	v_mov_b32_e32 v91, v131
	v_mov_b32_e32 v96, v131
	v_mov_b32_e32 v97, v131
	v_mov_b32_e32 v98, v131
	v_mov_b32_e32 v99, v131
	v_mov_b32_e32 v104, v131
	v_mov_b32_e32 v105, v131
	v_mov_b32_e32 v106, v131
	v_mov_b32_e32 v107, v131
	v_mov_b32_e32 v116, v131
	v_mov_b32_e32 v117, v131
	v_mov_b32_e32 v118, v131
	v_mov_b32_e32 v119, v131
	v_mov_b32_e32 v76, v131
	v_mov_b32_e32 v77, v131
	v_mov_b32_e32 v78, v131
	v_mov_b32_e32 v79, v131
	v_mov_b32_e32 v84, v131
	v_mov_b32_e32 v85, v131
	v_mov_b32_e32 v86, v131
	v_mov_b32_e32 v87, v131
	v_mov_b32_e32 v92, v131
	v_mov_b32_e32 v93, v131
	v_mov_b32_e32 v94, v131
	v_mov_b32_e32 v95, v131
	v_mov_b32_e32 v100, v131
	v_mov_b32_e32 v101, v131
	v_mov_b32_e32 v102, v131
	v_mov_b32_e32 v103, v131
	v_mov_b32_e32 v108, v131
	v_mov_b32_e32 v109, v131
	v_mov_b32_e32 v110, v131
	v_mov_b32_e32 v111, v131
	v_mov_b32_e32 v112, v131
	v_mov_b32_e32 v113, v131
	v_mov_b32_e32 v114, v131
	v_mov_b32_e32 v115, v131
	v_mov_b32_e32 v120, v131
	v_mov_b32_e32 v121, v131
	v_mov_b32_e32 v122, v131
	v_mov_b32_e32 v123, v131
	v_mov_b32_e32 v124, v131
	v_mov_b32_e32 v125, v131
	v_mov_b32_e32 v126, v131
	v_mov_b32_e32 v127, v131
	s_barrier
	s_branch .LBB0_1372

; #define PG8_STAGE(bufoff, gbase, voff) do { _Pragma("unroll") for (int _i = 0; _i < 2; ++_i) \
;         __builtin_amdgcn_global_load_lds((const unsigned*)((const char*)(gbase) + (voff)[_i]), (LAS unsigned*)(lds + (bufoff) + ldsw + _i * 8192), 16, 0, 0); } while (0)
; #define PG8_WAIT_V(n) asm volatile("s_waitcnt vmcnt(" #n ")" ::: "memory")
; #define PG8_BAR __builtin_amdgcn_s_barrier()
; template <class Epi>
; __device__ __forceinline__ void gemm_phase(LAS unsigned char* lds, const Gemm g, const Sched& S, const Epi& E) {
;     ...
;     PG8_STAGE(PG8_SB(0, 0), cB, voffB); PG8_STAGE(PG8_SB(0, 1), cB + hstepB, voffB); PG8_STAGE(PG8_SA(0, 0), cA, voffA); PG8_STAGE(PG8_SA(0, 1), cA + hstepA, voffA);
;     if (wr == 1) PG8_BAR;
;     PG8_WAIT_V(2); PG8_BAR;
;     PG8_STAGE(PG8_SB(1, 0), cB + kstep, voffB); PG8_STAGE(PG8_SA(1, 0), cA + kstep, voffA); PG8_STAGE(PG8_SB(1, 1), cB + hstepB + kstep, voffB);
;     PG8_WAIT_V(6); PG8_BAR;
.LBB0_1427:
	s_lshl_b32 s2, s2, 5
	s_and_b32 s2, s2, 0x60
	s_lshl_b32 s21, s3, 13
	s_lshl_b32 s24, s2, 7
	s_add_u32 s16, s34, 0x14900000
	s_mov_b64 s[18:19], 0x80
	s_addc_u32 s17, s35, 0
	s_add_i32 m0, s27, 0x18000
	v_lshl_add_u64 v[6:7], v[6:7], 0, s[18:19]
	global_load_lds_dwordx4 v[6:7], off
	v_lshl_add_u64 v[4:5], v[4:5], 0, s[18:19]
	s_add_i32 m0, s27, 0x1a000
	s_add_i32 s60, s27, 0x8000
	s_add_i32 s61, s27, 0xa000
	global_load_lds_dwordx4 v[4:5], off
	v_lshl_add_u64 v[0:1], v[0:1], 0, s[18:19]
	s_mov_b32 m0, s60
	s_add_u32 s22, s36, 0x80080
	global_load_lds_dwordx4 v[0:1], off
	v_lshl_add_u64 v[0:1], v[2:3], 0, s[18:19]
	s_mov_b32 m0, s61
	s_addc_u32 s23, s37, 0
	global_load_lds_dwordx4 v[0:1], off
	s_add_i32 m0, s27, 0x1c000
	v_lshl_add_u64 v[0:1], s[22:23], 0, v[130:131]
	global_load_lds_dwordx4 v[0:1], off
	v_lshl_add_u64 v[0:1], s[22:23], 0, v[134:135]
	s_add_i32 m0, s27, 0x1e000
	s_cmpk_lt_u32 s20, 0x100
	global_load_lds_dwordx4 v[0:1], off
	s_waitcnt vmcnt(8)
	s_barrier
	v_lshrrev_b32_e32 v1, 1, v8
	v_and_b32_e32 v1, 24, v1
	v_and_b32_e32 v0, 15, v8
	v_lshlrev_b32_e32 v2, 1, v1
	v_lshl_or_b32 v136, s3, 6, v0
	v_lshl_or_b32 v0, v0, 6, v2
	v_lshlrev_b32_e32 v2, 2, v8
	v_and_b32_e32 v2, 32, v2
	s_waitcnt vmcnt(6)
	v_bitop3_b32 v3, v0, s21, v2 bitop3:0xde
	v_bitop3_b32 v137, v0, s24, v2 bitop3:0xde
	s_cselect_b64 s[20:21], -1, 0
	s_add_i32 s62, 0, 0x10000
	s_add_i32 s63, 0, 0x14000
	v_or_b32_e32 v138, s2, v1
	v_add_u32_e32 v139, s62, v137
	v_add_u32_e32 v140, s63, v137
	v_add_u32_e32 v141, 0, v3
	s_barrier
	s_branch .LBB0_1430

; #define PG8_STAGE(bufoff, gbase, voff) do { _Pragma("unroll") for (int _i = 0; _i < 2; ++_i) \
;         __builtin_amdgcn_global_load_lds((const unsigned*)((const char*)(gbase) + (voff)[_i]), (LAS unsigned*)(lds + (bufoff) + ldsw + _i * 8192), 16, 0, 0); } while (0)
; #define PG8_WAIT_V(n) asm volatile("s_waitcnt vmcnt(" #n ")" ::: "memory")
; #define PG8_BAR __builtin_amdgcn_s_barrier()
; template <class Epi>
; __device__ __forceinline__ void gemm_phase(LAS unsigned char* lds, const Gemm g, const Sched& S, const Epi& E) {
;     ...
;     PG8_STAGE(PG8_SB(0, 0), cB, voffB); PG8_STAGE(PG8_SB(0, 1), cB + hstepB, voffB); PG8_STAGE(PG8_SA(0, 0), cA, voffA); PG8_STAGE(PG8_SA(0, 1), cA + hstepA, voffA);
;     if (wr == 1) PG8_BAR;
;     PG8_WAIT_V(2); PG8_BAR;
;     PG8_STAGE(PG8_SB(1, 0), cB + kstep, voffB); PG8_STAGE(PG8_SA(1, 0), cA + kstep, voffA); PG8_STAGE(PG8_SB(1, 1), cB + hstepB + kstep, voffB);
;     PG8_WAIT_V(6); PG8_BAR;
.LBB0_1721:
	s_add_u32 s2, s34, 0x9e00000
	s_addc_u32 s3, s35, 0
	s_lshl_b32 s4, s4, 5
	s_and_b32 s15, s4, 0x60
	s_mov_b64 s[4:5], 0x80
	s_add_i32 m0, s25, 0x18000
	v_lshl_add_u64 v[6:7], v[6:7], 0, s[4:5]
	s_lshl_b32 s14, s7, 13
	s_lshl_b32 s16, s15, 7
	global_load_lds_dwordx4 v[6:7], off
	v_lshl_add_u64 v[4:5], v[4:5], 0, s[4:5]
	s_add_i32 m0, s25, 0x1a000
	s_add_i32 s44, s25, 0x8000
	s_add_i32 s45, s25, 0xa000
	global_load_lds_dwordx4 v[4:5], off
	v_lshl_add_u64 v[0:1], v[0:1], 0, s[4:5]
	s_mov_b32 m0, s44
	s_add_u32 s8, s28, 0x40080
	global_load_lds_dwordx4 v[0:1], off
	v_lshl_add_u64 v[0:1], v[2:3], 0, s[4:5]
	s_mov_b32 m0, s45
	s_addc_u32 s9, s29, 0
	global_load_lds_dwordx4 v[0:1], off
	s_add_i32 m0, s25, 0x1c000
	v_lshl_add_u64 v[0:1], s[8:9], 0, v[130:131]
	global_load_lds_dwordx4 v[0:1], off
	v_lshl_add_u64 v[0:1], s[8:9], 0, v[134:135]
	s_add_i32 m0, s25, 0x1e000
	s_cmpk_lt_u32 s6, 0x100
	global_load_lds_dwordx4 v[0:1], off
	s_waitcnt vmcnt(8)
	s_barrier
	v_lshrrev_b32_e32 v1, 1, v8
	v_and_b32_e32 v1, 24, v1
	v_and_b32_e32 v0, 15, v8
	v_lshlrev_b32_e32 v2, 1, v1
	v_lshl_or_b32 v142, s7, 6, v0
	v_lshl_or_b32 v0, v0, 6, v2
	v_lshlrev_b32_e32 v2, 2, v8
	v_and_b32_e32 v2, 32, v2
	v_bitop3_b32 v3, v0, s14, v2 bitop3:0xde
	v_bitop3_b32 v143, v0, s16, v2 bitop3:0xde
	v_lshlrev_b32_e32 v0, 14, v9
	v_and_b32_e32 v0, 0xffff8000, v0
	v_or_b32_e32 v144, s15, v1
	v_lshl_add_u32 v0, v10, 11, v0
	v_and_b32_e32 v1, 1, v9
	v_lshl_or_b32 v0, v1, 6, v0
	v_lshl_add_u32 v136, v11, 1, v0
	v_lshlrev_b32_e32 v0, 14, v12
	v_and_b32_e32 v0, 0xffff8000, v0
	s_waitcnt vmcnt(6)
	v_lshl_add_u32 v0, v13, 11, v0
	v_and_b32_e32 v1, 1, v12
	s_cselect_b64 s[6:7], -1, 0
	v_lshl_or_b32 v0, v1, 6, v0
	s_add_i32 s46, 0, 0x10000
	s_add_i32 s47, 0, 0x14000
	v_mov_b32_e32 v137, v131
	v_lshl_add_u32 v138, v14, 1, v0
	v_mov_b32_e32 v139, v131
	v_add_u32_e32 v145, s46, v143
	v_add_u32_e32 v146, s47, v143
	v_add_u32_e32 v147, 0, v3
	s_movk_i32 s48, 0x4080
	s_movk_i32 s49, 0x1600
	s_barrier
	s_branch .LBB0_1724

; #define PG8_STAGE(bufoff, gbase, voff) do { _Pragma("unroll") for (int _i = 0; _i < 2; ++_i) \
;         __builtin_amdgcn_global_load_lds((const unsigned*)((const char*)(gbase) + (voff)[_i]), (LAS unsigned*)(lds + (bufoff) + ldsw + _i * 8192), 16, 0, 0); } while (0)
; #define PG8_WAIT_V(n) asm volatile("s_waitcnt vmcnt(" #n ")" ::: "memory")
; #define PG8_BAR __builtin_amdgcn_s_barrier()
; template <class Epi>
; __device__ __forceinline__ void gemm_phase(LAS unsigned char* lds, const Gemm g, const Sched& S, const Epi& E) {
;     ...
;     f32x4 acc[2][2][4][2];
; #pragma unroll
;     for (int a = 0; a < 2; ++a)
; #pragma unroll
;         for (int b = 0; b < 2; ++b)
; #pragma unroll
;             for (int m = 0; m < 4; ++m)
; #pragma unroll
;                 for (int n = 0; n < 2; ++n) acc[a][b][m][n] = (f32x4){0.f, 0.f, 0.f, 0.f};
;     bf16x8 At[4][2], B0[2][2], B1[2][2];
;     const char* cA = (const char*)g.A + (size_t)S.aoff(cur) * 2; const char* cB = (const char*)g.Bt + (size_t)S.boff(cur) * 2;
;     PG8_STAGE(PG8_SB(0, 0), cB, voffB); PG8_STAGE(PG8_SB(0, 1), cB + hstepB, voffB); PG8_STAGE(PG8_SA(0, 0), cA, voffA); PG8_STAGE(PG8_SA(0, 1), cA + hstepA, voffA);
;     if (wr == 1) PG8_BAR;
;     PG8_WAIT_V(2); PG8_BAR;
;     PG8_STAGE(PG8_SB(1, 0), cB + kstep, voffB); PG8_STAGE(PG8_SA(1, 0), cA + kstep, voffA); PG8_STAGE(PG8_SB(1, 1), cB + hstepB + kstep, voffB);
;     PG8_WAIT_V(6); PG8_BAR;
.LBB0_1815:
	s_mov_b64 s[16:17], 0x80
	s_and_b32 s41, s1, 3
	s_add_i32 m0, s47, 0x18000
	v_lshl_add_u64 v[6:7], v[6:7], 0, s[16:17]
	s_lshl_b32 s51, s40, 6
	s_lshl_b32 s3, s40, 13
	s_lshl_b32 s20, s41, 12
	global_load_lds_dwordx4 v[6:7], off
	v_lshl_add_u64 v[4:5], v[4:5], 0, s[16:17]
	s_add_i32 m0, s47, 0x1a000
	s_add_i32 s52, s47, 0x8000
	s_add_i32 s53, s47, 0xa000
	global_load_lds_dwordx4 v[4:5], off
	v_lshl_add_u64 v[0:1], v[0:1], 0, s[16:17]
	s_mov_b32 m0, s52
	s_add_u32 s18, s28, 0xb0080
	global_load_lds_dwordx4 v[0:1], off
	v_lshl_add_u64 v[0:1], v[2:3], 0, s[16:17]
	s_mov_b32 m0, s53
	s_addc_u32 s19, s29, 0
	global_load_lds_dwordx4 v[0:1], off
	s_add_i32 m0, s47, 0x1c000
	v_lshl_add_u64 v[0:1], s[18:19], 0, v[130:131]
	global_load_lds_dwordx4 v[0:1], off
	v_lshl_add_u64 v[0:1], s[18:19], 0, v[134:135]
	s_add_i32 m0, s47, 0x1e000
	v_and_b32_e32 v205, 15, v202
	global_load_lds_dwordx4 v[0:1], off
	s_waitcnt vmcnt(8)
	s_barrier
	v_and_b32_e32 v0, 48, v202
	v_lshlrev_b32_e32 v1, 2, v202
	v_lshl_or_b32 v0, v205, 6, v0
	v_and_b32_e32 v1, 32, v1
	v_bitop3_b32 v4, v0, s3, v1 bitop3:0xde
	v_bitop3_b32 v144, v0, s20, v1 bitop3:0xde
	v_lshrrev_b32_e32 v1, 1, v8
	v_mul_lo_u32 v0, v10, s2
	s_mov_b32 s3, 0xb000
	v_mad_u64_u32 v[0:1], s[22:23], v1, s3, v[0:1]
	v_or_b32_e32 v0, v0, v9
	s_mov_b64 s[20:21], 0xb0080
	v_add_lshl_u32 v0, v0, v11, 1
	v_mov_b32_e32 v1, v131
	v_lshl_add_u64 v[136:137], v[0:1], 0, s[20:21]
	v_lshrrev_b32_e32 v1, 1, v12
	v_mul_lo_u32 v0, v13, s2
	v_mad_u64_u32 v[0:1], s[2:3], v1, s3, v[0:1]
	v_or_b32_e32 v0, v0, v14
	s_waitcnt vmcnt(6)
	s_cmpk_lt_u32 s11, 0x100
	v_add_lshl_u32 v0, v0, v15, 1
	v_mov_b32_e32 v1, v131
	v_mov_b32_e32 v2, v131
	v_mov_b32_e32 v3, v131
	s_cselect_b64 s[18:19], -1, 0
	v_lshl_add_u64 v[138:139], v[0:1], 0, s[20:21]
	v_mov_b32_e32 v0, v131
	s_add_i32 s54, 0, 0x10000
	v_add_u32_e32 v145, 0, v4
	v_mov_b64_e32 v[6:7], v[2:3]
	v_mov_b64_e32 v[18:19], v[2:3]
	v_mov_b64_e32 v[22:23], v[2:3]
	v_mov_b64_e32 v[34:35], v[2:3]
	v_mov_b64_e32 v[38:39], v[2:3]
	v_mov_b64_e32 v[50:51], v[2:3]
	v_mov_b64_e32 v[54:55], v[2:3]
	v_mov_b64_e32 v[10:11], v[2:3]
	v_mov_b64_e32 v[14:15], v[2:3]
	v_mov_b64_e32 v[26:27], v[2:3]
	v_mov_b64_e32 v[30:31], v[2:3]
	v_mov_b64_e32 v[42:43], v[2:3]
	v_mov_b64_e32 v[46:47], v[2:3]
	v_mov_b64_e32 v[58:59], v[2:3]
	v_mov_b64_e32 v[62:63], v[2:3]
	v_mov_b64_e32 v[66:67], v[2:3]
	v_mov_b64_e32 v[70:71], v[2:3]
	v_mov_b64_e32 v[82:83], v[2:3]
	v_mov_b64_e32 v[86:87], v[2:3]
	v_mov_b64_e32 v[98:99], v[2:3]
	v_mov_b64_e32 v[102:103], v[2:3]
	v_mov_b64_e32 v[114:115], v[2:3]
	v_mov_b64_e32 v[118:119], v[2:3]
	v_mov_b64_e32 v[74:75], v[2:3]
	v_mov_b64_e32 v[78:79], v[2:3]
	v_mov_b64_e32 v[90:91], v[2:3]
	v_mov_b64_e32 v[94:95], v[2:3]
	v_mov_b64_e32 v[106:107], v[2:3]
	v_mov_b64_e32 v[110:111], v[2:3]
	v_mov_b64_e32 v[122:123], v[2:3]
	v_mov_b64_e32 v[126:127], v[2:3]
	s_sext_i32_i8 s0, s0
	v_or_b32_e32 v204, s51, v205
	s_mov_b32 s62, 0
	s_add_i32 s55, 0, 0x14000
	s_add_i32 s56, s47, 0xc000
	s_add_i32 s57, s47, 0xe000
	s_add_i32 s58, s54, s46
	v_mov_b64_e32 v[4:5], v[0:1]
	v_mov_b64_e32 v[16:17], v[0:1]
	v_mov_b64_e32 v[20:21], v[0:1]
	v_mov_b64_e32 v[32:33], v[0:1]
	v_mov_b64_e32 v[36:37], v[0:1]
	v_mov_b64_e32 v[48:49], v[0:1]
	v_mov_b64_e32 v[52:53], v[0:1]
	v_mov_b64_e32 v[8:9], v[0:1]
	v_mov_b64_e32 v[12:13], v[0:1]
	v_mov_b64_e32 v[24:25], v[0:1]
	v_mov_b64_e32 v[28:29], v[0:1]
	v_mov_b64_e32 v[40:41], v[0:1]
	v_mov_b64_e32 v[44:45], v[0:1]
	v_mov_b64_e32 v[56:57], v[0:1]
	v_mov_b64_e32 v[60:61], v[0:1]
	v_mov_b64_e32 v[64:65], v[0:1]
	v_mov_b64_e32 v[68:69], v[0:1]
	v_mov_b64_e32 v[80:81], v[0:1]
	v_mov_b64_e32 v[84:85], v[0:1]
	v_mov_b64_e32 v[96:97], v[0:1]
	v_mov_b64_e32 v[100:101], v[0:1]
	v_mov_b64_e32 v[112:113], v[0:1]
	v_mov_b64_e32 v[116:117], v[0:1]
	v_mov_b64_e32 v[72:73], v[0:1]
	v_mov_b64_e32 v[76:77], v[0:1]
	v_mov_b64_e32 v[88:89], v[0:1]
	v_mov_b64_e32 v[92:93], v[0:1]
	v_mov_b64_e32 v[104:105], v[0:1]
	v_mov_b64_e32 v[108:109], v[0:1]
	v_mov_b64_e32 v[120:121], v[0:1]
	v_mov_b64_e32 v[124:125], v[0:1]
	s_barrier
